# stack on the aligned version: attention epilogue gate-row wait below staging, 1/l once per row, row-max canonicalising v_max removed, GEMM restart stages issued before the first wait
# speedup vs baseline: 1.0041x; 1.0041x over previous
.LBB0_1417:
	v_rcp_f32_e32 v43, v43
	v_cmp_gt_u32_e32 vcc, 32, v188
	s_and_saveexec_b64 s[2:3], vcc
	v_lshl_add_u32 v44, v188, 2, s97
	ds_write_b32 v44, v43 offset:128
	s_or_b64 exec, exec, s[2:3]
	s_waitcnt lgkmcnt(0)
	ds_read_b128 v[44:47], v196 offset:128
	v_mov_b32_e32 v48, v80
	v_mov_b32_e32 v49, v96
	v_lshlrev_b32_e32 v43, 1, v193
	v_mov_b32_e32 v96, v81
	s_waitcnt lgkmcnt(0)
	v_lshl_add_u64 v[40:41], s[30:31], 0, v[40:41]
	v_pk_mul_f32 v[48:49], v[48:49], v[44:45] op_sel_hi:[1,0]
	v_lshl_add_u64 v[40:41], v[40:41], 0, s[6:7]
	v_cvt_pk_bf16_f32 v44, v48, v49
	v_lshlrev_b32_e32 v48, 9, v192
	v_add3_u32 v43, s74, v43, v48
	ds_write_b16 v43, v44
	ds_write_b16_d16_hi v43, v44 offset:64
	v_mov_b32_e32 v44, v45
	v_mov_b32_e32 v48, v82
	v_mov_b32_e32 v49, v98
	v_mov_b32_e32 v98, v83
	v_pk_mul_f32 v[44:45], v[96:97], v[44:45] op_sel_hi:[1,0]
	v_lshl_add_u64 v[40:41], v[40:41], 0, v[112:113]
	v_cvt_pk_bf16_f32 v44, v44, v45
	ds_write_b16 v43, v44 offset:128
	ds_write_b16_d16_hi v43, v44 offset:192
	v_mov_b32_e32 v44, v46
	s_andn2_b64 vcc, exec, s[60:61]
	s_mov_b64 s[34:35], 0
	v_pk_mul_f32 v[44:45], v[48:49], v[44:45] op_sel_hi:[1,0]
	s_nop 0
	v_cvt_pk_bf16_f32 v44, v44, v45
	ds_write_b16 v43, v44 offset:256
	ds_write_b16_d16_hi v43, v44 offset:320
	v_mov_b32_e32 v44, v47
	v_mov_b32_e32 v48, v84
	v_mov_b32_e32 v49, v100
	v_mov_b32_e32 v100, v85
	v_pk_mul_f32 v[44:45], v[98:99], v[44:45] op_sel_hi:[1,0]
	s_nop 0
	v_cvt_pk_bf16_f32 v44, v44, v45
	ds_write_b16 v43, v44 offset:384
	ds_write_b16_d16_hi v43, v44 offset:448
	ds_read_b128 v[44:47], v196 offset:160
	s_waitcnt lgkmcnt(0)
	s_nop 0
	v_pk_mul_f32 v[48:49], v[48:49], v[44:45] op_sel_hi:[1,0]
	s_nop 0
	v_cvt_pk_bf16_f32 v44, v48, v49
	ds_write_b16 v43, v44 offset:1024
	ds_write_b16_d16_hi v43, v44 offset:1088
	v_mov_b32_e32 v44, v45
	v_mov_b32_e32 v48, v86
	v_mov_b32_e32 v49, v102
	v_mov_b32_e32 v102, v87
	v_pk_mul_f32 v[44:45], v[100:101], v[44:45] op_sel_hi:[1,0]
	s_nop 0
	v_cvt_pk_bf16_f32 v44, v44, v45
	ds_write_b16 v43, v44 offset:1152
	ds_write_b16_d16_hi v43, v44 offset:1216
	v_mov_b32_e32 v44, v46
	s_nop 0
	v_pk_mul_f32 v[44:45], v[48:49], v[44:45] op_sel_hi:[1,0]
	s_nop 0
	v_cvt_pk_bf16_f32 v44, v44, v45
	ds_write_b16 v43, v44 offset:1280
	ds_write_b16_d16_hi v43, v44 offset:1344
	v_mov_b32_e32 v44, v47
	v_mov_b32_e32 v48, v88
	v_mov_b32_e32 v49, v104
	v_mov_b32_e32 v104, v89
	v_pk_mul_f32 v[44:45], v[102:103], v[44:45] op_sel_hi:[1,0]
	s_nop 0
	v_cvt_pk_bf16_f32 v44, v44, v45
	ds_write_b16 v43, v44 offset:1408
	ds_write_b16_d16_hi v43, v44 offset:1472
	ds_read_b128 v[44:47], v196 offset:192
	s_waitcnt lgkmcnt(0)
	s_nop 0
	v_pk_mul_f32 v[48:49], v[48:49], v[44:45] op_sel_hi:[1,0]
	s_nop 0
	v_cvt_pk_bf16_f32 v44, v48, v49
	ds_write_b16 v43, v44 offset:2048
	ds_write_b16_d16_hi v43, v44 offset:2112
	v_mov_b32_e32 v44, v45
	v_mov_b32_e32 v48, v90
	v_mov_b32_e32 v49, v106
	v_mov_b32_e32 v106, v91
	v_pk_mul_f32 v[44:45], v[104:105], v[44:45] op_sel_hi:[1,0]
	s_nop 0
	v_cvt_pk_bf16_f32 v44, v44, v45
	ds_write_b16 v43, v44 offset:2176
	ds_write_b16_d16_hi v43, v44 offset:2240
	v_mov_b32_e32 v44, v46
	s_nop 0
	v_pk_mul_f32 v[44:45], v[48:49], v[44:45] op_sel_hi:[1,0]
	s_nop 0
	v_cvt_pk_bf16_f32 v44, v44, v45
	ds_write_b16 v43, v44 offset:2304
	ds_write_b16_d16_hi v43, v44 offset:2368
	v_mov_b32_e32 v44, v47
	v_mov_b32_e32 v48, v92
	v_mov_b32_e32 v49, v108
	v_mov_b32_e32 v108, v93
	v_pk_mul_f32 v[44:45], v[106:107], v[44:45] op_sel_hi:[1,0]
	s_nop 0
	v_cvt_pk_bf16_f32 v44, v44, v45
	ds_write_b16 v43, v44 offset:2432
	ds_write_b16_d16_hi v43, v44 offset:2496
	ds_read_b128 v[44:47], v196 offset:224
	s_waitcnt lgkmcnt(0)
	s_nop 0
	v_pk_mul_f32 v[48:49], v[48:49], v[44:45] op_sel_hi:[1,0]
	s_nop 0
	v_cvt_pk_bf16_f32 v44, v48, v49
	ds_write_b16 v43, v44 offset:3072
	ds_write_b16_d16_hi v43, v44 offset:3136
	v_mov_b32_e32 v44, v45
	v_mov_b32_e32 v48, v94
	v_mov_b32_e32 v49, v110
	v_mov_b32_e32 v110, v95
	v_pk_mul_f32 v[44:45], v[108:109], v[44:45] op_sel_hi:[1,0]
	s_nop 0
	v_cvt_pk_bf16_f32 v44, v44, v45
	ds_write_b16 v43, v44 offset:3200
	ds_write_b16_d16_hi v43, v44 offset:3264
	v_mov_b32_e32 v44, v46
	s_nop 0
	v_pk_mul_f32 v[44:45], v[48:49], v[44:45] op_sel_hi:[1,0]
	s_nop 0
	v_cvt_pk_bf16_f32 v44, v44, v45
	ds_write_b16 v43, v44 offset:3328
	ds_write_b16_d16_hi v43, v44 offset:3392
	v_mov_b32_e32 v44, v47
	s_nop 0
	v_pk_mul_f32 v[44:45], v[110:111], v[44:45] op_sel_hi:[1,0]
	s_nop 0
	v_cvt_pk_bf16_f32 v44, v44, v45
	ds_write_b16 v43, v44 offset:3456
	ds_write_b16_d16_hi v43, v44 offset:3520
	s_waitcnt vmcnt(3)
	v_lshlrev_b32_e32 v50, 16, v36
	v_and_b32_e32 v51, 0xffff0000, v36
	v_add_u32_e32 v43, s74, v112
	s_waitcnt lgkmcnt(0)
	v_lshl_add_u32 v44, v42, 7, v43
	ds_read_b128 v[44:47], v44
	s_waitcnt lgkmcnt(0)
	v_lshlrev_b32_e32 v48, 16, v44
	v_and_b32_e32 v49, 0xffff0000, v44
	v_pk_mul_f32 v[48:49], v[50:51], v[48:49]
	v_lshlrev_b32_e32 v44, 16, v45
	v_cvt_pk_bf16_f32 v36, v48, v49
	v_and_b32_e32 v45, 0xffff0000, v45
	v_lshlrev_b32_e32 v48, 16, v37
	v_and_b32_e32 v49, 0xffff0000, v37
	v_pk_mul_f32 v[44:45], v[48:49], v[44:45]
	v_lshlrev_b32_e32 v48, 16, v38
	v_cvt_pk_bf16_f32 v37, v44, v45
	v_lshlrev_b32_e32 v44, 16, v46
	v_and_b32_e32 v45, 0xffff0000, v46
	v_and_b32_e32 v49, 0xffff0000, v38
	v_pk_mul_f32 v[44:45], v[48:49], v[44:45]
	v_lshlrev_b32_e32 v46, 16, v39
	v_cvt_pk_bf16_f32 v38, v44, v45
	v_lshlrev_b32_e32 v44, 16, v47
	v_and_b32_e32 v45, 0xffff0000, v47
	v_and_b32_e32 v47, 0xffff0000, v39
	v_pk_mul_f32 v[44:45], v[46:47], v[44:45]
	s_waitcnt vmcnt(2)
	v_lshlrev_b32_e32 v46, 16, v32
	v_cvt_pk_bf16_f32 v39, v44, v45
	global_store_dwordx4 v[40:41], v[36:39], off sc1
	s_nop 1
	v_add_u32_e32 v40, 8, v42
	v_lshl_add_u32 v36, v40, 7, v43
	ds_read_b128 v[36:39], v36
	v_and_b32_e32 v47, 0xffff0000, v32
	v_add_u32_e32 v40, s56, v40
	v_ashrrev_i32_e32 v41, 31, v40
	s_waitcnt lgkmcnt(0)
	v_lshlrev_b32_e32 v44, 16, v36
	v_and_b32_e32 v45, 0xffff0000, v36
	v_pk_mul_f32 v[44:45], v[46:47], v[44:45]
	v_lshlrev_b32_e32 v36, 16, v37
	v_cvt_pk_bf16_f32 v32, v44, v45
	v_and_b32_e32 v37, 0xffff0000, v37
	v_lshlrev_b32_e32 v44, 16, v33
	v_and_b32_e32 v45, 0xffff0000, v33
	v_pk_mul_f32 v[36:37], v[44:45], v[36:37]
	v_lshlrev_b32_e32 v44, 16, v34
	v_cvt_pk_bf16_f32 v33, v36, v37
	v_lshlrev_b32_e32 v36, 16, v38
	v_and_b32_e32 v37, 0xffff0000, v38
	v_and_b32_e32 v45, 0xffff0000, v34
	v_pk_mul_f32 v[36:37], v[44:45], v[36:37]
	v_lshlrev_b32_e32 v38, 16, v35
	v_cvt_pk_bf16_f32 v34, v36, v37
	v_lshlrev_b32_e32 v36, 16, v39
	v_and_b32_e32 v37, 0xffff0000, v39
	v_and_b32_e32 v39, 0xffff0000, v35
	v_pk_mul_f32 v[36:37], v[38:39], v[36:37]
	s_nop 0
	v_cvt_pk_bf16_f32 v35, v36, v37
	v_lshlrev_b64 v[36:37], 11, v[40:41]
	v_lshl_add_u64 v[36:37], s[30:31], 0, v[36:37]
	v_lshl_add_u64 v[36:37], v[36:37], 0, s[6:7]
	v_lshl_add_u64 v[36:37], v[36:37], 0, v[112:113]
	global_store_dwordx4 v[36:37], v[32:35], off sc1
	s_nop 1
	v_add_u32_e32 v36, 16, v42
	v_lshl_add_u32 v32, v36, 7, v43
	ds_read_b128 v[32:35], v32
	s_waitcnt vmcnt(3)
	v_lshlrev_b32_e32 v40, 16, v28
	v_and_b32_e32 v41, 0xffff0000, v28
	v_add_u32_e32 v36, s56, v36
	v_ashrrev_i32_e32 v37, 31, v36
	s_waitcnt lgkmcnt(0)
	v_lshlrev_b32_e32 v38, 16, v32
	v_and_b32_e32 v39, 0xffff0000, v32
	v_pk_mul_f32 v[38:39], v[40:41], v[38:39]
	v_lshlrev_b32_e32 v32, 16, v33
	v_cvt_pk_bf16_f32 v28, v38, v39
	v_and_b32_e32 v33, 0xffff0000, v33
	v_lshlrev_b32_e32 v38, 16, v29
	v_and_b32_e32 v39, 0xffff0000, v29
	v_pk_mul_f32 v[32:33], v[38:39], v[32:33]
	v_lshlrev_b32_e32 v38, 16, v30
	v_cvt_pk_bf16_f32 v29, v32, v33
	v_lshlrev_b32_e32 v32, 16, v34
	v_and_b32_e32 v33, 0xffff0000, v34
	v_and_b32_e32 v39, 0xffff0000, v30
	v_pk_mul_f32 v[32:33], v[38:39], v[32:33]
	v_lshlrev_b32_e32 v34, 16, v31
	v_cvt_pk_bf16_f32 v30, v32, v33
	v_lshlrev_b32_e32 v32, 16, v35
	v_and_b32_e32 v33, 0xffff0000, v35
	v_and_b32_e32 v35, 0xffff0000, v31
	v_pk_mul_f32 v[32:33], v[34:35], v[32:33]
	s_nop 0
	v_cvt_pk_bf16_f32 v31, v32, v33
	v_lshlrev_b64 v[32:33], 11, v[36:37]
	v_lshl_add_u64 v[32:33], s[30:31], 0, v[32:33]
	v_lshl_add_u64 v[32:33], v[32:33], 0, s[6:7]
	v_lshl_add_u64 v[32:33], v[32:33], 0, v[112:113]
	global_store_dwordx4 v[32:33], v[28:31], off sc1
	s_nop 1
	v_add_u32_e32 v32, 24, v42
	v_lshl_add_u32 v28, v32, 7, v43
	ds_read_b128 v[28:31], v28
	s_waitcnt vmcnt(3)
	v_lshlrev_b32_e32 v36, 16, v24
	v_and_b32_e32 v37, 0xffff0000, v24
	v_add_u32_e32 v32, s56, v32
	v_ashrrev_i32_e32 v33, 31, v32
	s_waitcnt lgkmcnt(0)
	v_lshlrev_b32_e32 v34, 16, v28
	v_and_b32_e32 v35, 0xffff0000, v28
	v_pk_mul_f32 v[34:35], v[36:37], v[34:35]
	v_lshlrev_b32_e32 v28, 16, v29
	v_cvt_pk_bf16_f32 v24, v34, v35
	v_and_b32_e32 v29, 0xffff0000, v29
	v_lshlrev_b32_e32 v34, 16, v25
	v_and_b32_e32 v35, 0xffff0000, v25
	v_pk_mul_f32 v[28:29], v[34:35], v[28:29]
	v_lshlrev_b32_e32 v34, 16, v26
	v_cvt_pk_bf16_f32 v25, v28, v29
	v_lshlrev_b32_e32 v28, 16, v30
	v_and_b32_e32 v29, 0xffff0000, v30
	v_and_b32_e32 v35, 0xffff0000, v26
	v_pk_mul_f32 v[28:29], v[34:35], v[28:29]
	v_lshlrev_b32_e32 v30, 16, v27
	v_cvt_pk_bf16_f32 v26, v28, v29
	v_lshlrev_b32_e32 v28, 16, v31
	v_and_b32_e32 v29, 0xffff0000, v31
	v_and_b32_e32 v31, 0xffff0000, v27
	v_pk_mul_f32 v[28:29], v[30:31], v[28:29]
	s_nop 0
	v_cvt_pk_bf16_f32 v27, v28, v29
	v_lshlrev_b64 v[28:29], 11, v[32:33]
	v_lshl_add_u64 v[28:29], s[30:31], 0, v[28:29]
	v_lshl_add_u64 v[28:29], v[28:29], 0, s[6:7]
	v_lshl_add_u64 v[28:29], v[28:29], 0, v[112:113]
	global_store_dwordx4 v[28:29], v[24:27], off sc1
	s_nop 1
	s_mov_b64 s[6:7], 0
	s_cbranch_vccnz .LBB0_1421
	s_waitcnt vmcnt(0) lgkmcnt(0)
	s_and_b64 s[34:35], s[4:5], exec

.LBB0_1503:
	s_movk_i32 s64, 0x2000
	v_rcp_f32_e32 v43, v43
	v_cmp_gt_u32_e32 vcc, 32, v188
	s_and_saveexec_b64 s[2:3], vcc
	v_lshl_add_u32 v44, v188, 2, s97
	ds_write_b32 v44, v43 offset:128
	s_or_b64 exec, exec, s[2:3]
	s_waitcnt lgkmcnt(0)
	ds_read_b128 v[44:47], v172 offset:128
	v_mov_b32_e32 v48, v80
	v_mov_b32_e32 v49, v96
	v_lshlrev_b32_e32 v43, 1, v193
	v_mov_b32_e32 v96, v81
	s_waitcnt lgkmcnt(0)
	v_lshl_add_u64 v[40:41], s[30:31], 0, v[40:41]
	v_pk_mul_f32 v[48:49], v[48:49], v[44:45] op_sel_hi:[1,0]
	v_lshl_add_u64 v[40:41], v[40:41], 0, s[4:5]
	v_cvt_pk_bf16_f32 v44, v48, v49
	v_lshlrev_b32_e32 v48, 9, v192
	v_add3_u32 v43, s74, v43, v48
	ds_write_b16 v43, v44
	ds_write_b16_d16_hi v43, v44 offset:64
	v_mov_b32_e32 v44, v45
	v_mov_b32_e32 v48, v82
	v_mov_b32_e32 v49, v98
	v_mov_b32_e32 v98, v83
	v_pk_mul_f32 v[44:45], v[96:97], v[44:45] op_sel_hi:[1,0]
	v_lshl_add_u64 v[40:41], v[40:41], 0, v[112:113]
	v_cvt_pk_bf16_f32 v44, v44, v45
	ds_write_b16 v43, v44 offset:128
	ds_write_b16_d16_hi v43, v44 offset:192
	v_mov_b32_e32 v44, v46
	s_andn2_b64 vcc, exec, s[60:61]
	v_pk_mul_f32 v[44:45], v[48:49], v[44:45] op_sel_hi:[1,0]
	s_nop 0
	v_cvt_pk_bf16_f32 v44, v44, v45
	ds_write_b16 v43, v44 offset:256
	ds_write_b16_d16_hi v43, v44 offset:320
	v_mov_b32_e32 v44, v47
	v_mov_b32_e32 v48, v84
	v_mov_b32_e32 v49, v100
	v_mov_b32_e32 v100, v85
	v_pk_mul_f32 v[44:45], v[98:99], v[44:45] op_sel_hi:[1,0]
	s_nop 0
	v_cvt_pk_bf16_f32 v44, v44, v45
	ds_write_b16 v43, v44 offset:384
	ds_write_b16_d16_hi v43, v44 offset:448
	ds_read_b128 v[44:47], v172 offset:160
	s_waitcnt lgkmcnt(0)
	s_nop 0
	v_pk_mul_f32 v[48:49], v[48:49], v[44:45] op_sel_hi:[1,0]
	s_nop 0
	v_cvt_pk_bf16_f32 v44, v48, v49
	ds_write_b16 v43, v44 offset:1024
	ds_write_b16_d16_hi v43, v44 offset:1088
	v_mov_b32_e32 v44, v45
	v_mov_b32_e32 v48, v86
	v_mov_b32_e32 v49, v102
	v_mov_b32_e32 v102, v87
	v_pk_mul_f32 v[44:45], v[100:101], v[44:45] op_sel_hi:[1,0]
	s_nop 0
	v_cvt_pk_bf16_f32 v44, v44, v45
	ds_write_b16 v43, v44 offset:1152
	ds_write_b16_d16_hi v43, v44 offset:1216
	v_mov_b32_e32 v44, v46
	s_nop 0
	v_pk_mul_f32 v[44:45], v[48:49], v[44:45] op_sel_hi:[1,0]
	s_nop 0
	v_cvt_pk_bf16_f32 v44, v44, v45
	ds_write_b16 v43, v44 offset:1280
	ds_write_b16_d16_hi v43, v44 offset:1344
	v_mov_b32_e32 v44, v47
	v_mov_b32_e32 v48, v88
	v_mov_b32_e32 v49, v104
	v_mov_b32_e32 v104, v89
	v_pk_mul_f32 v[44:45], v[102:103], v[44:45] op_sel_hi:[1,0]
	s_nop 0
	v_cvt_pk_bf16_f32 v44, v44, v45
	ds_write_b16 v43, v44 offset:1408
	ds_write_b16_d16_hi v43, v44 offset:1472
	ds_read_b128 v[44:47], v172 offset:192
	s_waitcnt lgkmcnt(0)
	s_nop 0
	v_pk_mul_f32 v[48:49], v[48:49], v[44:45] op_sel_hi:[1,0]
	s_nop 0
	v_cvt_pk_bf16_f32 v44, v48, v49
	ds_write_b16 v43, v44 offset:2048
	ds_write_b16_d16_hi v43, v44 offset:2112
	v_mov_b32_e32 v44, v45
	v_mov_b32_e32 v48, v90
	v_mov_b32_e32 v49, v106
	v_mov_b32_e32 v106, v91
	v_pk_mul_f32 v[44:45], v[104:105], v[44:45] op_sel_hi:[1,0]
	s_nop 0
	v_cvt_pk_bf16_f32 v44, v44, v45
	ds_write_b16 v43, v44 offset:2176
	ds_write_b16_d16_hi v43, v44 offset:2240
	v_mov_b32_e32 v44, v46
	s_nop 0
	v_pk_mul_f32 v[44:45], v[48:49], v[44:45] op_sel_hi:[1,0]
	s_nop 0
	v_cvt_pk_bf16_f32 v44, v44, v45
	ds_write_b16 v43, v44 offset:2304
	ds_write_b16_d16_hi v43, v44 offset:2368
	v_mov_b32_e32 v44, v47
	v_mov_b32_e32 v48, v92
	v_mov_b32_e32 v49, v108
	v_mov_b32_e32 v108, v93
	v_pk_mul_f32 v[44:45], v[106:107], v[44:45] op_sel_hi:[1,0]
	s_nop 0
	v_cvt_pk_bf16_f32 v44, v44, v45
	ds_write_b16 v43, v44 offset:2432
	ds_write_b16_d16_hi v43, v44 offset:2496
	ds_read_b128 v[44:47], v172 offset:224
	s_waitcnt lgkmcnt(0)
	s_nop 0
	v_pk_mul_f32 v[48:49], v[48:49], v[44:45] op_sel_hi:[1,0]
	s_nop 0
	v_cvt_pk_bf16_f32 v44, v48, v49
	ds_write_b16 v43, v44 offset:3072
	ds_write_b16_d16_hi v43, v44 offset:3136
	v_mov_b32_e32 v44, v45
	v_mov_b32_e32 v48, v94
	v_mov_b32_e32 v49, v110
	v_mov_b32_e32 v110, v95
	v_pk_mul_f32 v[44:45], v[108:109], v[44:45] op_sel_hi:[1,0]
	s_nop 0
	v_cvt_pk_bf16_f32 v44, v44, v45
	ds_write_b16 v43, v44 offset:3200
	ds_write_b16_d16_hi v43, v44 offset:3264
	v_mov_b32_e32 v44, v46
	s_nop 0
	v_pk_mul_f32 v[44:45], v[48:49], v[44:45] op_sel_hi:[1,0]
	s_nop 0
	v_cvt_pk_bf16_f32 v44, v44, v45
	ds_write_b16 v43, v44 offset:3328
	ds_write_b16_d16_hi v43, v44 offset:3392
	v_mov_b32_e32 v44, v47
	s_nop 0
	v_pk_mul_f32 v[44:45], v[110:111], v[44:45] op_sel_hi:[1,0]
	s_nop 0
	v_cvt_pk_bf16_f32 v44, v44, v45
	ds_write_b16 v43, v44 offset:3456
	ds_write_b16_d16_hi v43, v44 offset:3520
	s_waitcnt vmcnt(3)
	v_lshlrev_b32_e32 v50, 16, v36
	v_and_b32_e32 v51, 0xffff0000, v36
	v_add_u32_e32 v43, s74, v112
	s_waitcnt lgkmcnt(0)
	v_lshl_add_u32 v44, v42, 7, v43
	ds_read_b128 v[44:47], v44
	s_waitcnt lgkmcnt(0)
	v_lshlrev_b32_e32 v48, 16, v44
	v_and_b32_e32 v49, 0xffff0000, v44
	v_pk_mul_f32 v[48:49], v[50:51], v[48:49]
	v_lshlrev_b32_e32 v44, 16, v45
	v_cvt_pk_bf16_f32 v36, v48, v49
	v_and_b32_e32 v45, 0xffff0000, v45
	v_lshlrev_b32_e32 v48, 16, v37
	v_and_b32_e32 v49, 0xffff0000, v37
	v_pk_mul_f32 v[44:45], v[48:49], v[44:45]
	v_lshlrev_b32_e32 v48, 16, v38
	v_cvt_pk_bf16_f32 v37, v44, v45
	v_lshlrev_b32_e32 v44, 16, v46
	v_and_b32_e32 v45, 0xffff0000, v46
	v_and_b32_e32 v49, 0xffff0000, v38
	v_pk_mul_f32 v[44:45], v[48:49], v[44:45]
	v_lshlrev_b32_e32 v46, 16, v39
	v_cvt_pk_bf16_f32 v38, v44, v45
	v_lshlrev_b32_e32 v44, 16, v47
	v_and_b32_e32 v45, 0xffff0000, v47
	v_and_b32_e32 v47, 0xffff0000, v39
	v_pk_mul_f32 v[44:45], v[46:47], v[44:45]
	s_waitcnt vmcnt(2)
	v_lshlrev_b32_e32 v46, 16, v32
	v_cvt_pk_bf16_f32 v39, v44, v45
	global_store_dwordx4 v[40:41], v[36:39], off sc1
	s_nop 1
	v_add_u32_e32 v40, 8, v42
	v_lshl_add_u32 v36, v40, 7, v43
	ds_read_b128 v[36:39], v36
	v_and_b32_e32 v47, 0xffff0000, v32
	v_add_u32_e32 v40, s56, v40
	v_ashrrev_i32_e32 v41, 31, v40
	s_waitcnt lgkmcnt(0)
	v_lshlrev_b32_e32 v44, 16, v36
	v_and_b32_e32 v45, 0xffff0000, v36
	v_pk_mul_f32 v[44:45], v[46:47], v[44:45]
	v_lshlrev_b32_e32 v36, 16, v37
	v_cvt_pk_bf16_f32 v32, v44, v45
	v_and_b32_e32 v37, 0xffff0000, v37
	v_lshlrev_b32_e32 v44, 16, v33
	v_and_b32_e32 v45, 0xffff0000, v33
	v_pk_mul_f32 v[36:37], v[44:45], v[36:37]
	v_lshlrev_b32_e32 v44, 16, v34
	v_cvt_pk_bf16_f32 v33, v36, v37
	v_lshlrev_b32_e32 v36, 16, v38
	v_and_b32_e32 v37, 0xffff0000, v38
	v_and_b32_e32 v45, 0xffff0000, v34
	v_pk_mul_f32 v[36:37], v[44:45], v[36:37]
	v_lshlrev_b32_e32 v38, 16, v35
	v_cvt_pk_bf16_f32 v34, v36, v37
	v_lshlrev_b32_e32 v36, 16, v39
	v_and_b32_e32 v37, 0xffff0000, v39
	v_and_b32_e32 v39, 0xffff0000, v35
	v_pk_mul_f32 v[36:37], v[38:39], v[36:37]
	s_nop 0
	v_cvt_pk_bf16_f32 v35, v36, v37
	v_lshlrev_b64 v[36:37], 11, v[40:41]
	v_lshl_add_u64 v[36:37], s[30:31], 0, v[36:37]
	v_lshl_add_u64 v[36:37], v[36:37], 0, s[4:5]
	v_lshl_add_u64 v[36:37], v[36:37], 0, v[112:113]
	global_store_dwordx4 v[36:37], v[32:35], off sc1
	s_nop 1
	v_add_u32_e32 v36, 16, v42
	v_lshl_add_u32 v32, v36, 7, v43
	ds_read_b128 v[32:35], v32
	s_waitcnt vmcnt(3)
	v_lshlrev_b32_e32 v40, 16, v28
	v_and_b32_e32 v41, 0xffff0000, v28
	v_add_u32_e32 v36, s56, v36
	v_ashrrev_i32_e32 v37, 31, v36
	s_waitcnt lgkmcnt(0)
	v_lshlrev_b32_e32 v38, 16, v32
	v_and_b32_e32 v39, 0xffff0000, v32
	v_pk_mul_f32 v[38:39], v[40:41], v[38:39]
	v_lshlrev_b32_e32 v32, 16, v33
	v_cvt_pk_bf16_f32 v28, v38, v39
	v_and_b32_e32 v33, 0xffff0000, v33
	v_lshlrev_b32_e32 v38, 16, v29
	v_and_b32_e32 v39, 0xffff0000, v29
	v_pk_mul_f32 v[32:33], v[38:39], v[32:33]
	v_lshlrev_b32_e32 v38, 16, v30
	v_cvt_pk_bf16_f32 v29, v32, v33
	v_lshlrev_b32_e32 v32, 16, v34
	v_and_b32_e32 v33, 0xffff0000, v34
	v_and_b32_e32 v39, 0xffff0000, v30
	v_pk_mul_f32 v[32:33], v[38:39], v[32:33]
	v_lshlrev_b32_e32 v34, 16, v31
	v_cvt_pk_bf16_f32 v30, v32, v33
	v_lshlrev_b32_e32 v32, 16, v35
	v_and_b32_e32 v33, 0xffff0000, v35
	v_and_b32_e32 v35, 0xffff0000, v31
	v_pk_mul_f32 v[32:33], v[34:35], v[32:33]
	s_nop 0
	v_cvt_pk_bf16_f32 v31, v32, v33
	v_lshlrev_b64 v[32:33], 11, v[36:37]
	v_lshl_add_u64 v[32:33], s[30:31], 0, v[32:33]
	v_lshl_add_u64 v[32:33], v[32:33], 0, s[4:5]
	v_lshl_add_u64 v[32:33], v[32:33], 0, v[112:113]
	global_store_dwordx4 v[32:33], v[28:31], off sc1
	s_nop 1
	v_add_u32_e32 v32, 24, v42
	v_lshl_add_u32 v28, v32, 7, v43
	ds_read_b128 v[28:31], v28
	s_waitcnt vmcnt(3)
	v_lshlrev_b32_e32 v36, 16, v24
	v_and_b32_e32 v37, 0xffff0000, v24
	v_add_u32_e32 v32, s56, v32
	v_ashrrev_i32_e32 v33, 31, v32
	s_waitcnt lgkmcnt(0)
	v_lshlrev_b32_e32 v34, 16, v28
	v_and_b32_e32 v35, 0xffff0000, v28
	v_pk_mul_f32 v[34:35], v[36:37], v[34:35]
	v_lshlrev_b32_e32 v28, 16, v29
	v_cvt_pk_bf16_f32 v24, v34, v35
	v_and_b32_e32 v29, 0xffff0000, v29
	v_lshlrev_b32_e32 v34, 16, v25
	v_and_b32_e32 v35, 0xffff0000, v25
	v_pk_mul_f32 v[28:29], v[34:35], v[28:29]
	v_lshlrev_b32_e32 v34, 16, v26
	v_cvt_pk_bf16_f32 v25, v28, v29
	v_lshlrev_b32_e32 v28, 16, v30
	v_and_b32_e32 v29, 0xffff0000, v30
	v_and_b32_e32 v35, 0xffff0000, v26
	v_pk_mul_f32 v[28:29], v[34:35], v[28:29]
	v_lshlrev_b32_e32 v30, 16, v27
	v_cvt_pk_bf16_f32 v26, v28, v29
	v_lshlrev_b32_e32 v28, 16, v31
	v_and_b32_e32 v29, 0xffff0000, v31
	v_and_b32_e32 v31, 0xffff0000, v27
	v_pk_mul_f32 v[28:29], v[30:31], v[28:29]
	s_nop 0
	v_cvt_pk_bf16_f32 v27, v28, v29
	v_lshlrev_b64 v[28:29], 11, v[32:33]
	v_lshl_add_u64 v[28:29], s[30:31], 0, v[28:29]
	v_lshl_add_u64 v[28:29], v[28:29], 0, s[4:5]
	v_lshl_add_u64 v[28:29], v[28:29], 0, v[112:113]
	global_store_dwordx4 v[28:29], v[24:27], off sc1
	s_nop 1
	s_cbranch_vccnz .LBB0_1507
	s_waitcnt vmcnt(0) lgkmcnt(0)
	s_andn2_b64 s[2:3], s[34:35], exec
	s_and_b64 s[4:5], s[10:11], exec
	s_or_b64 s[34:35], s[2:3], s[4:5]
